# final RMSNorm pass: gain kept in registers, rows double-buffered, no waits on stores; prep shift@W loop unrolled x2 with a second register bank (next step's loads before this step's math)
# speedup vs baseline: 1.0531x; 1.0022x over previous
; #define WSP asglobal(p->ws)
; __device__ __forceinline__ void prep_phase(ParamsK p) {
;     ...
;     for (int t = gt; t < DEPTH * NCOL; t += NGT) { const int l = t / NCOL, cc = t % NCOL, w = cc >= INP, n = w ? cc - INP : cc;
;         const bf16_t* wrow = w ? (const bf16_t*)(WSP + WS_WUP) + ((size_t)l * FF2 + n) * DM : (const bf16_t*)(WSP + WS_WIN) + ((size_t)l * INP + n) * DM;
;         const float* sh = mod + (size_t)l * 9 * MODW + (w ? 3 : 0) * DM;
;         float acc[9];
; #pragma unroll
;         for (int r = 0; r < 9; ++r) acc[r] = 0.f;
;         for (int k = 0; k < DM; k += 8) { float wv[8]; unpack8(*(const u32x4*)(wrow + k), wv);
; #pragma unroll
;             for (int r = 0; r < 9; ++r) { const f32x4 s0 = *(const f32x4*)(sh + (size_t)r * MODW + k), s1 = *(const f32x4*)(sh + (size_t)r * MODW + k + 4);
;                 acc[r] += (s0[0] * wv[0] + s0[1] * wv[1]) + (s0[2] * wv[2] + s0[3] * wv[3]) + (s1[0] * wv[4] + s1[1] * wv[5]) + (s1[2] * wv[6] + s1[3] * wv[7]); } }
.LBB0_142:
	v_mul_hi_i32 v0, v12, s38
	v_add_u32_e32 v0, v0, v12
	v_lshrrev_b32_e32 v1, 31, v0
	v_ashrrev_i32_e32 v0, 13, v0
	v_add_u32_e32 v13, v0, v1
	v_mul_i32_i24_e32 v0, 0x2300, v13
	v_sub_u32_e32 v16, v12, v0
	v_cmp_lt_i32_e64 s[4:5], s39, v16
	v_cmp_gt_i32_e32 vcc, s40, v16
	s_and_saveexec_b64 s[36:37], vcc
	s_xor_b64 s[36:37], exec, s[36:37]
	v_mul_i32_i24_e32 v0, 0xd00, v13
	v_ashrrev_i32_e32 v1, 31, v0
	v_ashrrev_i32_e32 v17, 31, v16
	v_lshl_add_u64 v[0:1], v[0:1], 0, v[16:17]
	s_or_saveexec_b64 s[36:37], s[36:37]
	v_add_u32_e32 v20, 0xfffff300, v16
	v_mov_b64_e32 v[2:3], 0
	v_mov_b64_e32 v[4:5], s[0:1]
	s_xor_b64 exec, exec, s[36:37]
	v_mul_i32_i24_e32 v0, 0x1600, v13
	v_ashrrev_i32_e32 v1, 31, v0
	v_mov_b32_e32 v21, v15
	v_lshl_add_u64 v[0:1], v[0:1], 0, v[20:21]
	v_mov_b64_e32 v[2:3], 0xc00
	v_mov_b64_e32 v[4:5], s[8:9]
	s_or_b64 exec, exec, s[36:37]
	v_lshlrev_b64 v[0:1], 11, v[0:1]
	v_lshl_add_u64 v[28:29], v[4:5], 0, v[0:1]
	v_mul_i32_i24_e32 v0, 9, v13
	v_lshlrev_b32_e32 v14, 2, v2
	v_mad_i64_i32 v[0:1], s[36:37], v0, s41, v[14:15]
	v_mov_b32_e32 v26, 0
	v_lshl_add_u64 v[30:31], s[10:11], 0, v[0:1]
	s_mov_b32 s36, -8
	v_mov_b32_e32 v27, v26
	v_mov_b32_e32 v24, v26
	v_mov_b32_e32 v25, v26
	v_mov_b32_e32 v22, v26
	v_mov_b32_e32 v23, v26
	v_mov_b32_e32 v18, v26
	v_mov_b32_e32 v19, v26
	v_mov_b32_e32 v14, v26
	v_add_co_u32_e32 v34, vcc, s42, v30
	global_load_dwordx4 v[0:3], v[28:29], off
	s_nop 0
	v_addc_co_u32_e32 v35, vcc, -1, v31, vcc
	v_add_co_u32_e32 v48, vcc, s43, v30
	global_load_dwordx4 v[4:7], v[30:31], off
	global_load_dwordx4 v[8:11], v[30:31], off offset:-16
	v_addc_co_u32_e32 v49, vcc, -1, v31, vcc
	v_add_co_u32_e32 v56, vcc, s44, v30
	v_lshl_add_u64 v[32:33], v[30:31], 0, s[14:15]
	s_nop 0
	v_addc_co_u32_e32 v57, vcc, -1, v31, vcc
	v_add_co_u32_e32 v60, vcc, s45, v30
	v_lshl_add_u64 v[36:37], v[30:31], 0, s[20:21]
	s_nop 0
	v_addc_co_u32_e32 v61, vcc, -1, v31, vcc
	v_add_co_u32_e32 v68, vcc, s46, v30
	global_load_dwordx4 v[44:47], v[34:35], off offset:-16
	s_nop 0
	global_load_dwordx4 v[32:35], v[32:33], off offset:16
	v_addc_co_u32_e32 v69, vcc, -1, v31, vcc
	global_load_dwordx4 v[48:51], v[48:49], off offset:-16
	s_nop 0
	global_load_dwordx4 v[52:55], v[36:37], off offset:16
	v_add_co_u32_e32 v72, vcc, s47, v30
	v_lshl_add_u64 v[38:39], v[30:31], 0, s[22:23]
	s_nop 0
	v_addc_co_u32_e32 v73, vcc, -1, v31, vcc
	v_lshl_add_u64 v[40:41], v[30:31], 0, s[24:25]
	global_load_dwordx4 v[56:59], v[56:57], off offset:-16
	s_nop 0
	global_load_dwordx4 v[36:39], v[38:39], off offset:16
	s_nop 0
	global_load_dwordx4 v[60:63], v[60:61], off offset:-16
	s_nop 0
	global_load_dwordx4 v[64:67], v[40:41], off offset:16
	v_add_co_u32_e32 v80, vcc, s48, v30
	v_lshl_add_u64 v[42:43], v[30:31], 0, s[26:27]
	v_lshl_add_u64 v[76:77], v[30:31], 0, s[28:29]
	v_addc_co_u32_e32 v81, vcc, -1, v31, vcc
	global_load_dwordx4 v[68:71], v[68:69], off offset:-16
	s_nop 0
	global_load_dwordx4 v[40:43], v[42:43], off offset:16
	s_nop 0
	global_load_dwordx4 v[72:75], v[72:73], off offset:-16
	s_nop 0
	global_load_dwordx4 v[76:79], v[76:77], off offset:16
	v_add_co_u32_e32 v88, vcc, s49, v30
	v_lshl_add_u64 v[84:85], v[30:31], 0, s[30:31]
	v_lshl_add_u64 v[92:93], v[30:31], 0, s[34:35]
	v_addc_co_u32_e32 v89, vcc, -1, v31, vcc
	global_load_dwordx4 v[80:83], v[80:81], off offset:-16
	s_nop 0
	global_load_dwordx4 v[84:87], v[84:85], off offset:16
	s_nop 0
	global_load_dwordx4 v[88:91], v[88:89], off offset:-16
	s_nop 0
	global_load_dwordx4 v[92:95], v[92:93], off offset:16
	s_add_i32 s36, s36, 8
	v_lshl_add_u64 v[28:29], v[28:29], 0, 16
	v_lshl_add_u64 v[30:31], v[30:31], 0, 32
.LBB0_147:
	v_add_co_u32_e32 v166, vcc, s42, v30
	global_load_dwordx4 v[110:113], v[28:29], off
	s_nop 0
	v_addc_co_u32_e32 v167, vcc, -1, v31, vcc
	v_add_co_u32_e32 v180, vcc, s43, v30
	global_load_dwordx4 v[114:117], v[30:31], off
	global_load_dwordx4 v[118:121], v[30:31], off offset:-16
	v_addc_co_u32_e32 v181, vcc, -1, v31, vcc
	v_add_co_u32_e32 v188, vcc, s44, v30
	v_lshl_add_u64 v[164:165], v[30:31], 0, s[14:15]
	s_nop 0
	v_addc_co_u32_e32 v189, vcc, -1, v31, vcc
	v_add_co_u32_e32 v192, vcc, s45, v30
	v_lshl_add_u64 v[168:169], v[30:31], 0, s[20:21]
	s_nop 0
	v_addc_co_u32_e32 v193, vcc, -1, v31, vcc
	v_add_co_u32_e32 v200, vcc, s46, v30
	global_load_dwordx4 v[176:179], v[166:167], off offset:-16
	s_nop 0
	global_load_dwordx4 v[164:167], v[164:165], off offset:16
	v_addc_co_u32_e32 v201, vcc, -1, v31, vcc
	global_load_dwordx4 v[180:183], v[180:181], off offset:-16
	s_nop 0
	global_load_dwordx4 v[184:187], v[168:169], off offset:16
	v_add_co_u32_e32 v204, vcc, s47, v30
	v_lshl_add_u64 v[170:171], v[30:31], 0, s[22:23]
	s_nop 0
	v_addc_co_u32_e32 v205, vcc, -1, v31, vcc
	v_lshl_add_u64 v[172:173], v[30:31], 0, s[24:25]
	global_load_dwordx4 v[188:191], v[188:189], off offset:-16
	s_nop 0
	global_load_dwordx4 v[168:171], v[170:171], off offset:16
	s_nop 0
	global_load_dwordx4 v[192:195], v[192:193], off offset:-16
	s_nop 0
	global_load_dwordx4 v[196:199], v[172:173], off offset:16
	v_add_co_u32_e32 v212, vcc, s48, v30
	v_lshl_add_u64 v[174:175], v[30:31], 0, s[26:27]
	v_lshl_add_u64 v[208:209], v[30:31], 0, s[28:29]
	v_addc_co_u32_e32 v213, vcc, -1, v31, vcc
	global_load_dwordx4 v[200:203], v[200:201], off offset:-16
	s_nop 0
	global_load_dwordx4 v[172:175], v[174:175], off offset:16
	s_nop 0
	global_load_dwordx4 v[204:207], v[204:205], off offset:-16
	s_nop 0
	global_load_dwordx4 v[208:211], v[208:209], off offset:16
	v_add_co_u32_e32 v220, vcc, s49, v30
	v_lshl_add_u64 v[216:217], v[30:31], 0, s[30:31]
	v_lshl_add_u64 v[224:225], v[30:31], 0, s[34:35]
	v_addc_co_u32_e32 v221, vcc, -1, v31, vcc
	global_load_dwordx4 v[212:215], v[212:213], off offset:-16
	s_nop 0
	global_load_dwordx4 v[216:219], v[216:217], off offset:16
	s_nop 0
	global_load_dwordx4 v[220:223], v[220:221], off offset:-16
	s_nop 0
	global_load_dwordx4 v[224:227], v[224:225], off offset:16
	s_add_i32 s36, s36, 8
	v_lshl_add_u64 v[28:29], v[28:29], 0, 16
	v_lshl_add_u64 v[30:31], v[30:31], 0, 32
	s_waitcnt vmcnt(37)
; __device__ __forceinline__ void prep_phase(ParamsK p) {
;     ...
;         for (int k = 0; k < DM; k += 8) { float wv[8]; unpack8(*(const u32x4*)(wrow + k), wv);
; #pragma unroll
;             for (int r = 0; r < 9; ++r) { const f32x4 s0 = *(const f32x4*)(sh + (size_t)r * MODW + k), s1 = *(const f32x4*)(sh + (size_t)r * MODW + k + 4);
;                 acc[r] += (s0[0] * wv[0] + s0[1] * wv[1]) + (s0[2] * wv[2] + s0[3] * wv[3]) + (s1[0] * wv[4] + s1[1] * wv[5]) + (s1[2] * wv[6] + s1[3] * wv[7]); } }
	v_and_b32_e32 v96, 0xffff0000, v0
	v_lshlrev_b32_e32 v97, 16, v1
	v_lshlrev_b32_e32 v0, 16, v0
	v_and_b32_e32 v1, 0xffff0000, v1
	s_waitcnt vmcnt(36)
	v_mov_b32_e32 v100, v4
	s_waitcnt vmcnt(35)
	v_mov_b32_e32 v98, v9
	v_mov_b32_e32 v9, v11
	v_mov_b32_e32 v99, v10
	v_lshlrev_b32_e32 v11, 16, v3
	v_lshlrev_b32_e32 v10, 16, v2
	v_and_b32_e32 v3, 0xffff0000, v3
	v_and_b32_e32 v2, 0xffff0000, v2
	v_mov_b32_e32 v101, v6
	v_mov_b32_e32 v6, v5
	v_pk_mul_f32 v[4:5], v[8:9], v[0:1]
	v_pk_mul_f32 v[6:7], v[6:7], v[2:3]
	v_pk_fma_f32 v[4:5], v[98:99], v[96:97], v[4:5]
	v_pk_fma_f32 v[6:7], v[100:101], v[10:11], v[6:7]
	v_add_f32_e32 v9, v4, v5
	s_waitcnt vmcnt(34)
	v_mov_b32_e32 v98, v44
	v_mov_b32_e32 v44, v46
	s_waitcnt vmcnt(33)
	v_mov_b32_e32 v46, v32
	s_waitcnt vmcnt(32)
	v_mov_b32_e32 v99, v48
	v_mov_b32_e32 v48, v45
	v_mov_b32_e32 v45, v50
	v_mov_b32_e32 v50, v47
	v_mov_b32_e32 v32, v34
	s_waitcnt vmcnt(31)
	v_mov_b32_e32 v47, v52
	v_mov_b32_e32 v52, v33
	v_mov_b32_e32 v33, v54
	v_mov_b32_e32 v54, v35
	v_pk_mul_f32 v[4:5], v[48:49], v[96:97] op_sel_hi:[1,0]
	v_pk_mul_f32 v[34:35], v[50:51], v[0:1] op_sel:[0,1]
	v_mov_b32_e32 v8, v11
	v_pk_mul_f32 v[48:49], v[52:53], v[2:3] op_sel_hi:[1,0]
	v_pk_mul_f32 v[50:51], v[54:55], v[2:3] op_sel:[0,1]
	v_add_f32_e32 v6, v9, v6
	v_pk_fma_f32 v[4:5], v[98:99], v[0:1], v[4:5] op_sel_hi:[1,0,1]
	v_pk_fma_f32 v[34:35], v[44:45], v[96:97], v[34:35] op_sel:[0,1,0]
	s_waitcnt vmcnt(28)
	v_mov_b32_e32 v53, v60
	v_mov_b32_e32 v60, v57
	v_mov_b32_e32 v55, v62
	v_mov_b32_e32 v62, v59
	v_mov_b32_e32 v52, v56
	v_mov_b32_e32 v54, v58
	v_pk_fma_f32 v[44:45], v[46:47], v[10:11], v[48:49] op_sel_hi:[1,0,1]
	v_pk_fma_f32 v[32:33], v[32:33], v[8:9], v[50:51] op_sel_hi:[1,0,1]
	s_waitcnt vmcnt(27)
	v_mov_b32_e32 v57, v64
	v_mov_b32_e32 v64, v37
	v_add_f32_e32 v9, v7, v6
	v_pk_add_f32 v[4:5], v[4:5], v[34:35]
	v_pk_mul_f32 v[6:7], v[60:61], v[96:97] op_sel_hi:[1,0]
	v_pk_mul_f32 v[34:35], v[62:63], v[0:1] op_sel:[0,1]
	v_mov_b32_e32 v56, v36
	v_mov_b32_e32 v36, v38
	v_mov_b32_e32 v37, v66
	v_mov_b32_e32 v66, v39
	v_pk_mul_f32 v[38:39], v[64:65], v[2:3] op_sel_hi:[1,0]
	v_pk_add_f32 v[4:5], v[4:5], v[44:45]
	v_pk_fma_f32 v[6:7], v[52:53], v[0:1], v[6:7] op_sel_hi:[1,0,1]
	v_pk_fma_f32 v[34:35], v[54:55], v[96:97], v[34:35] op_sel:[0,1,0]
	s_waitcnt vmcnt(24)
	v_mov_b32_e32 v49, v72
	v_mov_b32_e32 v72, v69
	v_mov_b32_e32 v51, v74
	v_mov_b32_e32 v74, v71
	v_pk_mul_f32 v[46:47], v[66:67], v[2:3] op_sel:[0,1]
	v_mov_b32_e32 v48, v68
	v_mov_b32_e32 v50, v70
	v_pk_fma_f32 v[38:39], v[56:57], v[10:11], v[38:39] op_sel_hi:[1,0,1]
	s_waitcnt vmcnt(23)
	v_mov_b32_e32 v59, v76
	v_mov_b32_e32 v76, v41
	v_pk_add_f32 v[4:5], v[32:33], v[4:5]
	v_pk_add_f32 v[6:7], v[6:7], v[34:35]
	v_pk_mul_f32 v[32:33], v[72:73], v[96:97] op_sel_hi:[1,0]
	v_pk_mul_f32 v[34:35], v[74:75], v[0:1] op_sel:[0,1]
	v_mov_b32_e32 v58, v40
	v_mov_b32_e32 v40, v42
	v_pk_fma_f32 v[36:37], v[36:37], v[8:9], v[46:47] op_sel_hi:[1,0,1]
	v_mov_b32_e32 v41, v78
	v_mov_b32_e32 v78, v43
	v_pk_mul_f32 v[42:43], v[76:77], v[2:3] op_sel_hi:[1,0]
	v_pk_add_f32 v[26:27], v[26:27], v[4:5]
	v_pk_add_f32 v[4:5], v[6:7], v[38:39]
	v_pk_fma_f32 v[6:7], v[48:49], v[0:1], v[32:33] op_sel_hi:[1,0,1]
	v_pk_fma_f32 v[32:33], v[50:51], v[96:97], v[34:35] op_sel:[0,1,0]
	s_waitcnt vmcnt(20)
	v_mov_b32_e32 v47, v88
	v_mov_b32_e32 v88, v81
	v_mov_b32_e32 v53, v90
	v_mov_b32_e32 v90, v83
	v_pk_mul_f32 v[44:45], v[78:79], v[2:3] op_sel:[0,1]
	v_mov_b32_e32 v46, v80
	v_mov_b32_e32 v52, v82
	v_pk_fma_f32 v[34:35], v[58:59], v[10:11], v[42:43] op_sel_hi:[1,0,1]
	s_waitcnt vmcnt(19)
	v_mov_b32_e32 v55, v92
	v_mov_b32_e32 v92, v85
	v_pk_add_f32 v[4:5], v[36:37], v[4:5]
	v_pk_add_f32 v[6:7], v[6:7], v[32:33]
	v_pk_mul_f32 v[32:33], v[88:89], v[96:97] op_sel_hi:[1,0]
	v_pk_mul_f32 v[36:37], v[90:91], v[0:1] op_sel:[0,1]
	v_mov_b32_e32 v54, v84
	v_pk_fma_f32 v[38:39], v[40:41], v[8:9], v[44:45] op_sel_hi:[1,0,1]
	v_mov_b32_e32 v57, v94
	v_mov_b32_e32 v94, v87
	v_pk_mul_f32 v[40:41], v[92:93], v[2:3] op_sel_hi:[1,0]
	v_pk_add_f32 v[24:25], v[24:25], v[4:5]
	v_pk_add_f32 v[4:5], v[6:7], v[34:35]
	v_pk_fma_f32 v[0:1], v[46:47], v[0:1], v[32:33] op_sel_hi:[1,0,1]
	v_pk_fma_f32 v[6:7], v[52:53], v[96:97], v[36:37] op_sel:[0,1,0]
	v_mov_b32_e32 v56, v86
	v_pk_mul_f32 v[2:3], v[94:95], v[2:3] op_sel:[0,1]
	v_pk_fma_f32 v[10:11], v[54:55], v[10:11], v[40:41] op_sel_hi:[1,0,1]
	v_pk_add_f32 v[0:1], v[0:1], v[6:7]
	v_pk_fma_f32 v[2:3], v[56:57], v[8:9], v[2:3] op_sel_hi:[1,0,1]
	v_pk_add_f32 v[0:1], v[0:1], v[10:11]
	v_pk_add_f32 v[4:5], v[38:39], v[4:5]
	v_pk_add_f32 v[0:1], v[2:3], v[0:1]
	v_add_f32_e32 v14, v14, v9
	v_pk_add_f32 v[22:23], v[22:23], v[4:5]
	v_pk_add_f32 v[18:19], v[18:19], v[0:1]
	v_add_co_u32_e32 v34, vcc, s42, v30
	global_load_dwordx4 v[0:3], v[28:29], off
	s_nop 0
	v_addc_co_u32_e32 v35, vcc, -1, v31, vcc
	v_add_co_u32_e32 v48, vcc, s43, v30
	global_load_dwordx4 v[4:7], v[30:31], off
	global_load_dwordx4 v[8:11], v[30:31], off offset:-16
	v_addc_co_u32_e32 v49, vcc, -1, v31, vcc
	v_add_co_u32_e32 v56, vcc, s44, v30
	v_lshl_add_u64 v[32:33], v[30:31], 0, s[14:15]
	s_nop 0
	v_addc_co_u32_e32 v57, vcc, -1, v31, vcc
	v_add_co_u32_e32 v60, vcc, s45, v30
	v_lshl_add_u64 v[36:37], v[30:31], 0, s[20:21]
	s_nop 0
	v_addc_co_u32_e32 v61, vcc, -1, v31, vcc
	v_add_co_u32_e32 v68, vcc, s46, v30
	global_load_dwordx4 v[44:47], v[34:35], off offset:-16
	s_nop 0
	global_load_dwordx4 v[32:35], v[32:33], off offset:16
	v_addc_co_u32_e32 v69, vcc, -1, v31, vcc
	global_load_dwordx4 v[48:51], v[48:49], off offset:-16
	s_nop 0
	global_load_dwordx4 v[52:55], v[36:37], off offset:16
	v_add_co_u32_e32 v72, vcc, s47, v30
	v_lshl_add_u64 v[38:39], v[30:31], 0, s[22:23]
	s_nop 0
	v_addc_co_u32_e32 v73, vcc, -1, v31, vcc
	v_lshl_add_u64 v[40:41], v[30:31], 0, s[24:25]
	global_load_dwordx4 v[56:59], v[56:57], off offset:-16
	s_nop 0
	global_load_dwordx4 v[36:39], v[38:39], off offset:16
	s_nop 0
	global_load_dwordx4 v[60:63], v[60:61], off offset:-16
	s_nop 0
	global_load_dwordx4 v[64:67], v[40:41], off offset:16
	v_add_co_u32_e32 v80, vcc, s48, v30
	v_lshl_add_u64 v[42:43], v[30:31], 0, s[26:27]
	v_lshl_add_u64 v[76:77], v[30:31], 0, s[28:29]
	v_addc_co_u32_e32 v81, vcc, -1, v31, vcc
	global_load_dwordx4 v[68:71], v[68:69], off offset:-16
	s_nop 0
	global_load_dwordx4 v[40:43], v[42:43], off offset:16
	s_nop 0
	global_load_dwordx4 v[72:75], v[72:73], off offset:-16
	s_nop 0
	global_load_dwordx4 v[76:79], v[76:77], off offset:16
	v_add_co_u32_e32 v88, vcc, s49, v30
	v_lshl_add_u64 v[84:85], v[30:31], 0, s[30:31]
	v_lshl_add_u64 v[92:93], v[30:31], 0, s[34:35]
	v_addc_co_u32_e32 v89, vcc, -1, v31, vcc
	global_load_dwordx4 v[80:83], v[80:81], off offset:-16
	s_nop 0
	global_load_dwordx4 v[84:87], v[84:85], off offset:16
	s_nop 0
	global_load_dwordx4 v[88:91], v[88:89], off offset:-16
	s_nop 0
	global_load_dwordx4 v[92:95], v[92:93], off offset:16
	s_add_i32 s36, s36, 8
	v_lshl_add_u64 v[28:29], v[28:29], 0, 16
	s_cmpk_gt_u32 s36, 0x3f7
	v_lshl_add_u64 v[30:31], v[30:31], 0, 32
	s_waitcnt vmcnt(37)
; __device__ __forceinline__ void prep_phase(ParamsK p) {
;     ...
;         for (int k = 0; k < DM; k += 8) { float wv[8]; unpack8(*(const u32x4*)(wrow + k), wv);
; #pragma unroll
;             for (int r = 0; r < 9; ++r) { const f32x4 s0 = *(const f32x4*)(sh + (size_t)r * MODW + k), s1 = *(const f32x4*)(sh + (size_t)r * MODW + k + 4);
;                 acc[r] += (s0[0] * wv[0] + s0[1] * wv[1]) + (s0[2] * wv[2] + s0[3] * wv[3]) + (s1[0] * wv[4] + s1[1] * wv[5]) + (s1[2] * wv[6] + s1[3] * wv[7]); } }
; #pragma unroll
;         for (int r = 0; r < 9; ++r) BIAS[((size_t)(l * 2 + w) * 9 + r) * FF2 + n] = acc[r]; }
	v_and_b32_e32 v228, 0xffff0000, v110
	v_lshlrev_b32_e32 v229, 16, v111
	v_lshlrev_b32_e32 v110, 16, v110
	v_and_b32_e32 v111, 0xffff0000, v111
	s_waitcnt vmcnt(36)
	v_mov_b32_e32 v232, v114
	s_waitcnt vmcnt(35)
	v_mov_b32_e32 v230, v119
	v_mov_b32_e32 v119, v121
	v_mov_b32_e32 v231, v120
	v_lshlrev_b32_e32 v121, 16, v113
	v_lshlrev_b32_e32 v120, 16, v112
	v_and_b32_e32 v113, 0xffff0000, v113
	v_and_b32_e32 v112, 0xffff0000, v112
	v_mov_b32_e32 v233, v116
	v_mov_b32_e32 v116, v115
	v_pk_mul_f32 v[114:115], v[118:119], v[110:111]
	v_pk_mul_f32 v[116:117], v[116:117], v[112:113]
	v_pk_fma_f32 v[114:115], v[230:231], v[228:229], v[114:115]
	v_pk_fma_f32 v[116:117], v[232:233], v[120:121], v[116:117]
	v_add_f32_e32 v119, v114, v115
	s_waitcnt vmcnt(34)
	v_mov_b32_e32 v230, v176
	v_mov_b32_e32 v176, v178
	s_waitcnt vmcnt(33)
	v_mov_b32_e32 v178, v164
	s_waitcnt vmcnt(32)
	v_mov_b32_e32 v231, v180
	v_mov_b32_e32 v180, v177
	v_mov_b32_e32 v177, v182
	v_mov_b32_e32 v182, v179
	v_mov_b32_e32 v164, v166
	s_waitcnt vmcnt(31)
	v_mov_b32_e32 v179, v184
	v_mov_b32_e32 v184, v165
	v_mov_b32_e32 v165, v186
	v_mov_b32_e32 v186, v167
	v_pk_mul_f32 v[114:115], v[180:181], v[228:229] op_sel_hi:[1,0]
	v_pk_mul_f32 v[166:167], v[182:183], v[110:111] op_sel:[0,1]
	v_mov_b32_e32 v118, v121
	v_pk_mul_f32 v[180:181], v[184:185], v[112:113] op_sel_hi:[1,0]
	v_pk_mul_f32 v[182:183], v[186:187], v[112:113] op_sel:[0,1]
	v_add_f32_e32 v116, v119, v116
	v_pk_fma_f32 v[114:115], v[230:231], v[110:111], v[114:115] op_sel_hi:[1,0,1]
	v_pk_fma_f32 v[166:167], v[176:177], v[228:229], v[166:167] op_sel:[0,1,0]
	s_waitcnt vmcnt(28)
	v_mov_b32_e32 v185, v192
	v_mov_b32_e32 v192, v189
	v_mov_b32_e32 v187, v194
	v_mov_b32_e32 v194, v191
	v_mov_b32_e32 v184, v188
	v_mov_b32_e32 v186, v190
	v_pk_fma_f32 v[176:177], v[178:179], v[120:121], v[180:181] op_sel_hi:[1,0,1]
	v_pk_fma_f32 v[164:165], v[164:165], v[118:119], v[182:183] op_sel_hi:[1,0,1]
	s_waitcnt vmcnt(27)
	v_mov_b32_e32 v189, v196
	v_mov_b32_e32 v196, v169
	v_add_f32_e32 v119, v117, v116
	v_pk_add_f32 v[114:115], v[114:115], v[166:167]
	v_pk_mul_f32 v[116:117], v[192:193], v[228:229] op_sel_hi:[1,0]
	v_pk_mul_f32 v[166:167], v[194:195], v[110:111] op_sel:[0,1]
	v_mov_b32_e32 v188, v168
	v_mov_b32_e32 v168, v170
	v_mov_b32_e32 v169, v198
	v_mov_b32_e32 v198, v171
	v_pk_mul_f32 v[170:171], v[196:197], v[112:113] op_sel_hi:[1,0]
	v_pk_add_f32 v[114:115], v[114:115], v[176:177]
	v_pk_fma_f32 v[116:117], v[184:185], v[110:111], v[116:117] op_sel_hi:[1,0,1]
	v_pk_fma_f32 v[166:167], v[186:187], v[228:229], v[166:167] op_sel:[0,1,0]
	s_waitcnt vmcnt(24)
	v_mov_b32_e32 v181, v204
	v_mov_b32_e32 v204, v201
	v_mov_b32_e32 v183, v206
	v_mov_b32_e32 v206, v203
	v_pk_mul_f32 v[178:179], v[198:199], v[112:113] op_sel:[0,1]
	v_mov_b32_e32 v180, v200
	v_mov_b32_e32 v182, v202
	v_pk_fma_f32 v[170:171], v[188:189], v[120:121], v[170:171] op_sel_hi:[1,0,1]
	s_waitcnt vmcnt(23)
	v_mov_b32_e32 v191, v208
	v_mov_b32_e32 v208, v173
	v_pk_add_f32 v[114:115], v[164:165], v[114:115]
	v_pk_add_f32 v[116:117], v[116:117], v[166:167]
	v_pk_mul_f32 v[164:165], v[204:205], v[228:229] op_sel_hi:[1,0]
	v_pk_mul_f32 v[166:167], v[206:207], v[110:111] op_sel:[0,1]
	v_mov_b32_e32 v190, v172
	v_mov_b32_e32 v172, v174
	v_pk_fma_f32 v[168:169], v[168:169], v[118:119], v[178:179] op_sel_hi:[1,0,1]
	v_mov_b32_e32 v173, v210
	v_mov_b32_e32 v210, v175
	v_pk_mul_f32 v[174:175], v[208:209], v[112:113] op_sel_hi:[1,0]
	v_pk_add_f32 v[26:27], v[26:27], v[114:115]
	v_pk_add_f32 v[114:115], v[116:117], v[170:171]
	v_pk_fma_f32 v[116:117], v[180:181], v[110:111], v[164:165] op_sel_hi:[1,0,1]
	v_pk_fma_f32 v[164:165], v[182:183], v[228:229], v[166:167] op_sel:[0,1,0]
	s_waitcnt vmcnt(20)
	v_mov_b32_e32 v179, v220
	v_mov_b32_e32 v220, v213
	v_mov_b32_e32 v185, v222
	v_mov_b32_e32 v222, v215
	v_pk_mul_f32 v[176:177], v[210:211], v[112:113] op_sel:[0,1]
	v_mov_b32_e32 v178, v212
	v_mov_b32_e32 v184, v214
	v_pk_fma_f32 v[166:167], v[190:191], v[120:121], v[174:175] op_sel_hi:[1,0,1]
	s_waitcnt vmcnt(19)
	v_mov_b32_e32 v187, v224
	v_mov_b32_e32 v224, v217
	v_pk_add_f32 v[114:115], v[168:169], v[114:115]
	v_pk_add_f32 v[116:117], v[116:117], v[164:165]
	v_pk_mul_f32 v[164:165], v[220:221], v[228:229] op_sel_hi:[1,0]
	v_pk_mul_f32 v[168:169], v[222:223], v[110:111] op_sel:[0,1]
	v_mov_b32_e32 v186, v216
	v_pk_fma_f32 v[170:171], v[172:173], v[118:119], v[176:177] op_sel_hi:[1,0,1]
	v_mov_b32_e32 v189, v226
	v_mov_b32_e32 v226, v219
	v_pk_mul_f32 v[172:173], v[224:225], v[112:113] op_sel_hi:[1,0]
	v_pk_add_f32 v[24:25], v[24:25], v[114:115]
	v_pk_add_f32 v[114:115], v[116:117], v[166:167]
	v_pk_fma_f32 v[110:111], v[178:179], v[110:111], v[164:165] op_sel_hi:[1,0,1]
	v_pk_fma_f32 v[116:117], v[184:185], v[228:229], v[168:169] op_sel:[0,1,0]
	v_mov_b32_e32 v188, v218
	v_pk_mul_f32 v[112:113], v[226:227], v[112:113] op_sel:[0,1]
	v_pk_fma_f32 v[120:121], v[186:187], v[120:121], v[172:173] op_sel_hi:[1,0,1]
	v_pk_add_f32 v[110:111], v[110:111], v[116:117]
	v_pk_fma_f32 v[112:113], v[188:189], v[118:119], v[112:113] op_sel_hi:[1,0,1]
	v_pk_add_f32 v[110:111], v[110:111], v[120:121]
	v_pk_add_f32 v[114:115], v[170:171], v[114:115]
	v_pk_add_f32 v[110:111], v[112:113], v[110:111]
	v_add_f32_e32 v14, v14, v119
	v_pk_add_f32 v[22:23], v[22:23], v[114:115]
	v_pk_add_f32 v[18:19], v[18:19], v[110:111]
	s_cbranch_scc0 .LBB0_147
	s_waitcnt vmcnt(0)
	v_cndmask_b32_e64 v1, 0, 1, s[4:5]
	v_cndmask_b32_e64 v0, v16, v20, s[4:5]
	v_lshl_or_b32 v1, v13, 1, v1
	v_mul_i32_i24_e32 v2, 9, v1
	v_ashrrev_i32_e32 v1, 31, v0
	v_lshl_add_u64 v[0:1], v[0:1], 2, s[6:7]
	v_mad_i64_i32 v[0:1], s[4:5], v2, s51, v[0:1]
	v_add_co_u32_e32 v2, vcc, 0x5000, v0
	global_store_dword v[0:1], v26, off
	s_nop 0
	v_addc_co_u32_e32 v3, vcc, 0, v1, vcc
	global_store_dword v[2:3], v27, off offset:2048
	v_add_co_u32_e32 v2, vcc, 0xb000, v0
	v_add_u32_e32 v12, s56, v12
	s_nop 0
	v_addc_co_u32_e32 v3, vcc, 0, v1, vcc
	global_store_dword v[2:3], v24, off
	v_add_co_u32_e32 v2, vcc, 0x10000, v0
	s_nop 1
	v_addc_co_u32_e32 v3, vcc, 0, v1, vcc
	global_store_dword v[2:3], v25, off offset:2048
	v_add_co_u32_e32 v2, vcc, 0x16000, v0
	s_nop 1
	v_addc_co_u32_e32 v3, vcc, 0, v1, vcc
	global_store_dword v[2:3], v22, off
	v_add_co_u32_e32 v2, vcc, 0x1b000, v0
	s_nop 1
	v_addc_co_u32_e32 v3, vcc, 0, v1, vcc
	global_store_dword v[2:3], v23, off offset:2048
	v_add_co_u32_e32 v2, vcc, 0x21000, v0
	s_nop 1
	v_addc_co_u32_e32 v3, vcc, 0, v1, vcc
	global_store_dword v[2:3], v18, off
	v_add_co_u32_e32 v2, vcc, 0x26000, v0
	s_nop 1
	v_addc_co_u32_e32 v3, vcc, 0, v1, vcc
	v_add_co_u32_e32 v0, vcc, 0x2c000, v0
	global_store_dword v[2:3], v19, off offset:2048
	s_nop 0
	v_addc_co_u32_e32 v1, vcc, 0, v1, vcc
	v_cmp_lt_i32_e32 vcc, s52, v12
	s_or_b64 s[12:13], vcc, s[12:13]
	global_store_dword v[0:1], v14, off
	s_andn2_b64 exec, exec, s[12:13]
	s_cbranch_execnz .LBB0_142

; __device__ __forceinline__ int otid() { int t = threadIdx.x; asm volatile("" : "+v"(t)); return t; }
; __device__ __forceinline__ void final_norm_phase(float* x, const float* g) {
;     const int tid = otid(), lane = tid & 63, wave = __builtin_amdgcn_readfirstlane(tid >> 6);
;     const int gw = blockIdx.x * 8 + wave, NGW = gridDim.x * 8;
;     for (int row = gw; row < TL; row += NGW) {
;         float* src = x + (size_t)row * DM;
;         f32x4 v[4]; float ss = 0.f;
; #pragma unroll
;         for (int j = 0; j < 4; ++j) { v[j] = *(const f32x4*)(src + lane * 4 + 256 * j); ss += (v[j][0] * v[j][0] + v[j][1] * v[j][1]) + (v[j][2] * v[j][2] + v[j][3] * v[j][3]); }
.LBB0_1357:
	v_readlane_b32 s1, v252, 1
	v_readfirstlane_b32 s0, v163
	s_ashr_i32 s0, s0, 6
	s_add_i32 s0, s0, s1
	s_cmp_gt_i32 s0, 0xffff
	s_cbranch_scc1 .LBB0_1360
	v_and_b32_e32 v0, 64, v228
	v_add_u32_e32 v0, 64, v0
	v_xor_b32_e32 v1, 1, v228
	v_cmp_lt_i32_e32 vcc, v1, v0
	s_load_dwordx4 s[4:7], s[96:97], 0xb0
	s_ashr_i32 s1, s0, 31
	v_cndmask_b32_e32 v1, v228, v1, vcc
	v_lshlrev_b32_e32 v4, 2, v1
	v_xor_b32_e32 v1, 2, v228
	v_cmp_lt_i32_e32 vcc, v1, v0
	v_mov_b32_e32 v3, 0
	s_lshl_b64 s[2:3], s[0:1], 12
	v_cndmask_b32_e32 v1, v228, v1, vcc
	v_lshlrev_b32_e32 v5, 2, v1
	v_xor_b32_e32 v1, 4, v228
	v_cmp_lt_i32_e32 vcc, v1, v0
	s_waitcnt lgkmcnt(0)
	s_add_u32 s2, s6, s2
	s_addc_u32 s3, s7, s3
	v_cndmask_b32_e32 v1, v228, v1, vcc
	v_lshlrev_b32_e32 v6, 2, v1
	v_xor_b32_e32 v1, 8, v228
	v_cmp_lt_i32_e32 vcc, v1, v0
	s_ashr_i32 s63, s62, 31
	v_mov_b32_e32 v10, 0x358637bd
	v_cndmask_b32_e32 v1, v228, v1, vcc
	v_lshlrev_b32_e32 v7, 2, v1
	v_xor_b32_e32 v1, 16, v228
	v_cmp_lt_i32_e32 vcc, v1, v0
	s_mov_b32 s1, 0x800000
	s_nop 0
	v_cndmask_b32_e32 v1, v228, v1, vcc
	v_lshlrev_b32_e32 v8, 2, v1
	v_xor_b32_e32 v1, 32, v228
	v_cmp_lt_i32_e32 vcc, v1, v0
	s_nop 1
	v_cndmask_b32_e32 v0, v228, v1, vcc
	v_lshlrev_b32_e32 v9, 2, v0
	v_lshlrev_b32_e32 v0, 4, v163
	v_and_b32_e32 v2, 0x3f0, v0
	v_lshl_add_u64 v[0:1], s[4:5], 0, v[2:3]
	v_and_b32_e32 v2, 63, v163
	v_lshlrev_b32_e32 v2, 4, v2
	v_lshl_add_u64 v[2:3], s[2:3], 0, v[2:3]
	s_mov_b64 s[2:3], 0x800
	v_lshl_add_u64 v[2:3], v[2:3], 0, s[2:3]
	s_lshl_b64 s[2:3], s[62:63], 12
	global_load_dwordx4 v[48:51], v[0:1], off
	global_load_dwordx4 v[52:55], v[0:1], off offset:1024
	global_load_dwordx4 v[56:59], v[0:1], off offset:2048
	global_load_dwordx4 v[60:63], v[0:1], off offset:3072
	global_load_dwordx4 v[12:15], v[2:3], off offset:-2048
	global_load_dwordx4 v[16:19], v[2:3], off offset:-1024
	global_load_dwordx4 v[20:23], v[2:3], off offset:1024
	global_load_dwordx4 v[24:27], v[2:3], off
	s_waitcnt vmcnt(0)
; __device__ __forceinline__ void final_norm_phase(float* x, const float* g) {
;     ...
;     for (int row = gw; row < TL; row += NGW) {
;         float* src = x + (size_t)row * DM;
;         f32x4 v[4]; float ss = 0.f;
; #pragma unroll
;         for (int j = 0; j < 4; ++j) { v[j] = *(const f32x4*)(src + lane * 4 + 256 * j); ss += (v[j][0] * v[j][0] + v[j][1] * v[j][1]) + (v[j][2] * v[j][2] + v[j][3] * v[j][3]); }
;         const float rstd = rsqrtf(wave_sum(ss) * (1.f / DM) + 1e-6f);
; #pragma unroll
;         for (int j = 0; j < 4; ++j) { const int c = lane * 4 + 256 * j; const f32x4 g4 = *(const f32x4*)(g + c); *(f32x4*)(src + c) = v[j] * rstd * g4; }
;     }
.LBB0_1359:
	s_add_i32 s0, s0, s62
	s_cmp_lt_i32 s0, 0x10000
	s_cselect_b32 s4, s2, 0
	s_cselect_b32 s5, s3, 0
	v_lshl_add_u64 v[80:81], v[2:3], 0, s[4:5]
	global_load_dwordx4 v[64:67], v[80:81], off offset:-2048
	global_load_dwordx4 v[68:71], v[80:81], off offset:-1024
	global_load_dwordx4 v[72:75], v[80:81], off offset:1024
	global_load_dwordx4 v[76:79], v[80:81], off
	s_waitcnt vmcnt(8)
	v_pk_mul_f32 v[32:33], v[14:15], v[14:15]
	v_pk_mul_f32 v[34:35], v[12:13], v[12:13]
	v_pk_mul_f32 v[36:37], v[18:19], v[18:19]
	v_pk_mul_f32 v[38:39], v[16:17], v[16:17]
	v_pk_mov_b32 v[44:45], v[34:35], v[32:33] op_sel:[1,0]
	v_mov_b32_e32 v35, v33
	v_pk_mov_b32 v[32:33], v[38:39], v[36:37] op_sel:[1,0]
	v_mov_b32_e32 v39, v37
	v_mul_f32_e32 v43, v21, v21
	v_mul_f32_e32 v40, v25, v25
	v_mul_f32_e32 v42, v27, v27
	v_pk_add_f32 v[34:35], v[44:45], v[34:35]
	v_pk_add_f32 v[32:33], v[32:33], v[38:39]
	v_mul_f32_e32 v11, v20, v20
	v_mul_f32_e32 v46, v22, v22
	v_mul_f32_e32 v47, v23, v23
	v_pk_fma_f32 v[36:37], v[24:25], v[24:25], v[40:41] op_sel_hi:[1,1,0]
	v_pk_fma_f32 v[40:41], v[26:27], v[26:27], v[42:43] op_sel_hi:[1,1,0]
	v_pk_add_f32 v[34:35], v[34:35], v[34:35] op_sel:[0,1] op_sel_hi:[1,0]
	v_pk_add_f32 v[32:33], v[32:33], v[32:33] op_sel:[0,1] op_sel_hi:[1,0]
	v_mov_b32_e32 v37, v46
	v_mov_b32_e32 v41, v47
	v_mov_b32_e32 v35, v11
	v_mov_b32_e32 v33, v43
	v_pk_add_f32 v[36:37], v[36:37], v[40:41]
	v_pk_add_f32 v[32:33], v[34:35], v[32:33]
	s_nop 0
	v_pk_add_f32 v[32:33], v[32:33], v[36:37]
	s_nop 0
	v_add_f32_e32 v11, v32, v33
	ds_bpermute_b32 v32, v4, v11
	s_waitcnt lgkmcnt(0)
	v_add_f32_e32 v11, v11, v32
	ds_bpermute_b32 v32, v5, v11
	s_waitcnt lgkmcnt(0)
	v_add_f32_e32 v11, v11, v32
	ds_bpermute_b32 v32, v6, v11
	s_waitcnt lgkmcnt(0)
	v_add_f32_e32 v11, v11, v32
	ds_bpermute_b32 v32, v7, v11
	s_waitcnt lgkmcnt(0)
	v_add_f32_e32 v11, v11, v32
	ds_bpermute_b32 v32, v8, v11
	s_waitcnt lgkmcnt(0)
	v_add_f32_e32 v11, v11, v32
	ds_bpermute_b32 v32, v9, v11
	s_waitcnt lgkmcnt(0)
	v_add_f32_e32 v11, v11, v32
	v_fmamk_f32 v11, v11, 0x3a800000, v10
	v_mul_f32_e32 v32, 0x4b800000, v11
	v_cmp_gt_f32_e32 vcc, s1, v11
	s_nop 1
	v_cndmask_b32_e32 v11, v11, v32, vcc
	v_rsq_f32_e32 v11, v11
	s_nop 0
	v_mul_f32_e32 v32, 0x45800000, v11
	v_cndmask_b32_e32 v32, v11, v32, vcc
	v_pk_mul_f32 v[12:13], v[12:13], v[32:33] op_sel_hi:[1,0]
	v_pk_mul_f32 v[14:15], v[14:15], v[32:33] op_sel_hi:[1,0]
	v_pk_mul_f32 v[12:13], v[48:49], v[12:13]
	v_pk_mul_f32 v[14:15], v[50:51], v[14:15]
	v_pk_mul_f32 v[16:17], v[16:17], v[32:33] op_sel_hi:[1,0]
	v_pk_mul_f32 v[18:19], v[18:19], v[32:33] op_sel_hi:[1,0]
	v_pk_mul_f32 v[16:17], v[52:53], v[16:17]
	v_pk_mul_f32 v[18:19], v[54:55], v[18:19]
	v_pk_mul_f32 v[24:25], v[24:25], v[32:33] op_sel_hi:[1,0]
	v_pk_mul_f32 v[26:27], v[26:27], v[32:33] op_sel_hi:[1,0]
	v_pk_mul_f32 v[24:25], v[56:57], v[24:25]
	v_pk_mul_f32 v[26:27], v[58:59], v[26:27]
	v_pk_mul_f32 v[20:21], v[20:21], v[32:33] op_sel_hi:[1,0]
	v_pk_mul_f32 v[22:23], v[22:23], v[32:33] op_sel_hi:[1,0]
	v_pk_mul_f32 v[20:21], v[60:61], v[20:21]
	v_pk_mul_f32 v[22:23], v[62:63], v[22:23]
	global_store_dwordx4 v[2:3], v[12:15], off offset:-2048
	global_store_dwordx4 v[2:3], v[16:19], off offset:-1024
	global_store_dwordx4 v[2:3], v[24:27], off
	global_store_dwordx4 v[2:3], v[20:23], off offset:1024
	s_cmp_lt_i32 s0, 0x10000
	s_cbranch_scc0 .Lfn_done
	s_add_i32 s0, s0, s62
	s_cmp_lt_i32 s0, 0x10000
	s_cselect_b32 s4, s2, 0
	s_cselect_b32 s5, s3, 0
	v_lshl_add_u64 v[2:3], v[80:81], 0, s[4:5]
	global_load_dwordx4 v[12:15], v[2:3], off offset:-2048
	global_load_dwordx4 v[16:19], v[2:3], off offset:-1024
	global_load_dwordx4 v[20:23], v[2:3], off offset:1024
	global_load_dwordx4 v[24:27], v[2:3], off
	s_waitcnt vmcnt(8)
	v_pk_mul_f32 v[32:33], v[66:67], v[66:67]
	v_pk_mul_f32 v[34:35], v[64:65], v[64:65]
	v_pk_mul_f32 v[36:37], v[70:71], v[70:71]
	v_pk_mul_f32 v[38:39], v[68:69], v[68:69]
	v_pk_mov_b32 v[44:45], v[34:35], v[32:33] op_sel:[1,0]
	v_mov_b32_e32 v35, v33
	v_pk_mov_b32 v[32:33], v[38:39], v[36:37] op_sel:[1,0]
	v_mov_b32_e32 v39, v37
	v_mul_f32_e32 v43, v73, v73
	v_mul_f32_e32 v40, v77, v77
	v_mul_f32_e32 v42, v79, v79
	v_pk_add_f32 v[34:35], v[44:45], v[34:35]
	v_pk_add_f32 v[32:33], v[32:33], v[38:39]
	v_mul_f32_e32 v11, v72, v72
	v_mul_f32_e32 v46, v74, v74
	v_mul_f32_e32 v47, v75, v75
	v_pk_fma_f32 v[36:37], v[76:77], v[76:77], v[40:41] op_sel_hi:[1,1,0]
	v_pk_fma_f32 v[40:41], v[78:79], v[78:79], v[42:43] op_sel_hi:[1,1,0]
	v_pk_add_f32 v[34:35], v[34:35], v[34:35] op_sel:[0,1] op_sel_hi:[1,0]
	v_pk_add_f32 v[32:33], v[32:33], v[32:33] op_sel:[0,1] op_sel_hi:[1,0]
	v_mov_b32_e32 v37, v46
	v_mov_b32_e32 v41, v47
	v_mov_b32_e32 v35, v11
	v_mov_b32_e32 v33, v43
	v_pk_add_f32 v[36:37], v[36:37], v[40:41]
	v_pk_add_f32 v[32:33], v[34:35], v[32:33]
	s_nop 0
	v_pk_add_f32 v[32:33], v[32:33], v[36:37]
	s_nop 0
	v_add_f32_e32 v11, v32, v33
	ds_bpermute_b32 v32, v4, v11
	s_waitcnt lgkmcnt(0)
	v_add_f32_e32 v11, v11, v32
	ds_bpermute_b32 v32, v5, v11
	s_waitcnt lgkmcnt(0)
	v_add_f32_e32 v11, v11, v32
	ds_bpermute_b32 v32, v6, v11
	s_waitcnt lgkmcnt(0)
	v_add_f32_e32 v11, v11, v32
	ds_bpermute_b32 v32, v7, v11
	s_waitcnt lgkmcnt(0)
	v_add_f32_e32 v11, v11, v32
	ds_bpermute_b32 v32, v8, v11
	s_waitcnt lgkmcnt(0)
	v_add_f32_e32 v11, v11, v32
	ds_bpermute_b32 v32, v9, v11
	s_waitcnt lgkmcnt(0)
	v_add_f32_e32 v11, v11, v32
	v_fmamk_f32 v11, v11, 0x3a800000, v10
	v_mul_f32_e32 v32, 0x4b800000, v11
	v_cmp_gt_f32_e32 vcc, s1, v11
	s_nop 1
	v_cndmask_b32_e32 v11, v11, v32, vcc
	v_rsq_f32_e32 v11, v11
	s_nop 0
	v_mul_f32_e32 v32, 0x45800000, v11
	v_cndmask_b32_e32 v32, v11, v32, vcc
	v_pk_mul_f32 v[64:65], v[64:65], v[32:33] op_sel_hi:[1,0]
	v_pk_mul_f32 v[66:67], v[66:67], v[32:33] op_sel_hi:[1,0]
	v_pk_mul_f32 v[64:65], v[48:49], v[64:65]
	v_pk_mul_f32 v[66:67], v[50:51], v[66:67]
	v_pk_mul_f32 v[68:69], v[68:69], v[32:33] op_sel_hi:[1,0]
	v_pk_mul_f32 v[70:71], v[70:71], v[32:33] op_sel_hi:[1,0]
	v_pk_mul_f32 v[68:69], v[52:53], v[68:69]
	v_pk_mul_f32 v[70:71], v[54:55], v[70:71]
	v_pk_mul_f32 v[76:77], v[76:77], v[32:33] op_sel_hi:[1,0]
	v_pk_mul_f32 v[78:79], v[78:79], v[32:33] op_sel_hi:[1,0]
	v_pk_mul_f32 v[76:77], v[56:57], v[76:77]
	v_pk_mul_f32 v[78:79], v[58:59], v[78:79]
	v_pk_mul_f32 v[72:73], v[72:73], v[32:33] op_sel_hi:[1,0]
	v_pk_mul_f32 v[74:75], v[74:75], v[32:33] op_sel_hi:[1,0]
	v_pk_mul_f32 v[72:73], v[60:61], v[72:73]
	v_pk_mul_f32 v[74:75], v[62:63], v[74:75]
	global_store_dwordx4 v[80:81], v[64:67], off offset:-2048
	global_store_dwordx4 v[80:81], v[68:71], off offset:-1024
	global_store_dwordx4 v[80:81], v[76:79], off
	global_store_dwordx4 v[80:81], v[72:75], off offset:1024
	s_cmp_lt_i32 s0, 0x10000
	s_cbranch_scc1 .LBB0_1359
.Lfn_done:
	s_waitcnt vmcnt(0)
.LBB0_1360:
	s_endpgm
